# MFMA-first segment head: the 8 exp2 that opened each attention half-iteration after the barrier now run in front of the barrier (back-edge block / end of previous half / once before the loop)
# speedup vs baseline: 1.0128x; 1.0015x over previous
; #define EXP4(P, B) do { P[B] = __builtin_amdgcn_exp2f(P[B]); P[B + 1] = __builtin_amdgcn_exp2f(P[B + 1]); P[B + 2] = __builtin_amdgcn_exp2f(P[B + 2]); P[B + 3] = __builtin_amdgcn_exp2f(P[B + 3]); } while (0)
; #define SLOAD(i, k0) do { sr_[i].vs = BLD(rV, goff_kv, (k0) * 128); sr_[i].ks = BLD(rK, goff_kv, (k0) * 128); if (krt) sr_[i].kr = BLD(rR, goff_kr, (k0) * 64); } while (0)
; #define SWRITE(b, voff, i) do { *(bf16x8*)(V_lds + (voff) + vst0) = sr_[i].vs; *(bf16x8*)(K_lds + (b) * SHM_K + kst0) = sr_[i].ks; \
;     if (krt) *(bf16x8*)(K_lds + (b) * SHM_K + kst1) = sr_[i].kr; } while (0)
; #define SWAIT() do { asm volatile("s_waitcnt vmcnt(3)" ::: "memory"); } while (0)
; template <int KB, bool HASY>
; __device__ __forceinline__ void phaseA(f32x16& X0, f32x16& X1, f32x16& Y0, f32x16& Y1, bf16x8& pa0, bf16x8& pa1, bf16x8& pa2, bf16x8& pa3,
;                                        const bf16x8* qr, const f32x16& negm, int kaddr, VFr& vf, int vb, float& l_reg) {
;     ...
;   if (HASY) { EXP4(Y0, 0); EXP4(Y0, 4); }
; __device__ __forceinline__ void attn_unit(const bf16_t* __restrict__ Qb, const bf16_t* __restrict__ KNh, const bf16_t* __restrict__ KRb, const bf16_t* __restrict__ Vh,
;                                           bf16_t* __restrict__ Ob, int nkeys, char* lds, int tid_in) {
;     ...
;   SLOAD(SE, 0); asm volatile("s_waitcnt vmcnt(0)" ::: "memory"); SWRITE(0, 0, SE); __syncthreads();
;   phaseA<0, false>(pA0, pA1, pB0, pB1, pa0, pa1, pa2, pa3, qr, negm, kaddr, vf, vb0, l_reg);
;   alA = decide<true>(rowmax32(pA0, pA1), pA0, pA1, m_reg, negm);
;   SLOAD(SO, KVBLK); if (2 < NT) SLOAD(SE, 2 * KVBLK);
;   SWAIT(); SWRITE(1, SHM_V, SO); __syncthreads();
;   for (int j = 1; j + 1 < NT; j += 2) {
;     phaseA<1, true>(pB0, pB1, pA0, pA1, pa0, pa1, pa2, pa3, qr, negm, kaddr, vf, vb0 + vprev, l_reg);
.LBB0_244:
	s_or_b64 exec, exec, s[18:19]
	s_waitcnt vmcnt(3)
	s_waitcnt vmcnt(3)
	ds_write_b128 v187, v[34:37] offset:8192
	s_waitcnt vmcnt(2)
	ds_write_b128 v188, v[38:41] offset:37888
	v_add_u32_e32 v34, v45, v44
	s_and_saveexec_b64 s[18:19], vcc
	s_xor_b64 s[18:19], exec, s[18:19]
	v_add_u32_e32 v34, v45, v44
	s_andn2_saveexec_b64 s[18:19], s[18:19]
	v_add_u32_e32 v35, 0, v34
	ds_write_b128 v35, v[158:161] offset:38016
	s_or_b64 exec, exec, s[18:19]
	v_max_f32_e32 v36, v46, v46
	v_max_f32_e32 v0, v0, v0
	v_and_b32_e32 v35, 63, v42
	v_max_f32_e32 v0, v0, v36
	v_sub_f32_e32 v67, v3, v0
	v_lshlrev_b32_e32 v3, 4, v35
	v_sub_f32_e32 v68, v4, v0
	v_sub_f32_e32 v66, v2, v0
	v_lshlrev_b32_e32 v2, 3, v35
	v_and_b32_e32 v3, 0xc0, v3
	v_lshlrev_b32_e32 v4, 1, v35
	v_add_f32_e32 v189, 0, v0
	v_sub_f32_e32 v97, v33, v0
	v_sub_f32_e32 v96, v32, v0
	v_sub_f32_e32 v95, v31, v0
	v_sub_f32_e32 v94, v30, v0
	v_sub_f32_e32 v93, v29, v0
	v_sub_f32_e32 v92, v28, v0
	v_sub_f32_e32 v91, v27, v0
	v_sub_f32_e32 v90, v26, v0
	v_sub_f32_e32 v89, v25, v0
	v_sub_f32_e32 v88, v24, v0
	v_sub_f32_e32 v87, v23, v0
	v_sub_f32_e32 v86, v22, v0
	v_sub_f32_e32 v85, v21, v0
	v_sub_f32_e32 v84, v20, v0
	v_sub_f32_e32 v83, v19, v0
	v_sub_f32_e32 v82, v18, v0
	v_sub_f32_e32 v81, v17, v0
	v_sub_f32_e32 v80, v16, v0
	v_sub_f32_e32 v79, v15, v0
	v_sub_f32_e32 v78, v14, v0
	v_sub_f32_e32 v77, v13, v0
	v_sub_f32_e32 v76, v12, v0
	v_sub_f32_e32 v75, v11, v0
	v_sub_f32_e32 v74, v10, v0
	v_sub_f32_e32 v73, v9, v0
	v_sub_f32_e32 v72, v8, v0
	v_sub_f32_e32 v71, v7, v0
	v_sub_f32_e32 v70, v6, v0
	v_sub_f32_e32 v69, v5, v0
	v_and_b32_e32 v0, 0x3fffffc0, v42
	v_and_or_b32 v3, v2, 24, v3
	v_and_b32_e32 v4, 32, v4
	v_and_b32_e32 v2, 0x100, v2
	s_cmp_lg_u32 0, -1
	v_lshl_add_u32 v0, v0, 2, 0
	v_or3_b32 v2, v3, v4, v2
	s_cselect_b32 s19, 0, 0
	v_mov_b32_e32 v14, v1
	v_mov_b32_e32 v15, v1
	v_add_u32_e32 v192, s19, v2
	v_lshl_add_u32 v183, v182, 2, v0
	v_lshl_add_u32 v179, v181, 4, v0
	v_mov_b32_e32 v0, v1
	v_mov_b32_e32 v2, v1
	v_mov_b32_e32 v3, v1
	v_mov_b32_e32 v4, v1
	v_mov_b32_e32 v5, v1
	v_mov_b32_e32 v6, v1
	v_mov_b32_e32 v7, v1
	v_mov_b32_e32 v8, v1
	v_mov_b32_e32 v9, v1
	v_mov_b32_e32 v10, v1
	v_mov_b32_e32 v11, v1
	v_mov_b32_e32 v12, v1
	v_mov_b32_e32 v13, v1
	v_mov_b64_e32 v[32:33], v[14:15]
	v_xor_b32_e32 v50, 0x80000000, v189
	v_mov_b64_e32 v[30:31], v[12:13]
	v_mov_b64_e32 v[28:29], v[10:11]
	v_mov_b64_e32 v[26:27], v[8:9]
	v_mov_b64_e32 v[24:25], v[6:7]
	v_mov_b64_e32 v[22:23], v[4:5]
	v_mov_b64_e32 v[20:21], v[2:3]
	v_mov_b64_e32 v[18:19], v[0:1]
	v_mov_b64_e32 v[16:17], v[14:15]
	v_and_b32_e32 v178, 0xffffffe0, v43
	s_mov_b32 s39, 4
	s_mov_b32 s18, 0
	v_cmp_gt_u32_e64 s[40:41], 32, v35
	v_mov_b32_e32 v194, 0
	s_movk_i32 s53, 0x2000
	s_mov_b32 s52, 0x8000
	s_movk_i32 s68, 0x4000
	v_add_u32_e32 v193, 0, v34
	v_mov_b64_e32 v[14:15], v[12:13]
	v_mov_b64_e32 v[12:13], v[10:11]
	v_mov_b64_e32 v[10:11], v[8:9]
	v_mov_b64_e32 v[8:9], v[6:7]
	v_mov_b64_e32 v[6:7], v[4:5]
	v_mov_b64_e32 v[4:5], v[2:3]
	v_mov_b64_e32 v[2:3], v[0:1]
	s_movk_i32 s69, 0x4000
	v_mov_b32_e32 v51, v50
	v_mov_b32_e32 v52, v50
	v_mov_b32_e32 v53, v50
	v_mov_b32_e32 v54, v50
	v_mov_b32_e32 v55, v50
	v_mov_b32_e32 v56, v50
	v_mov_b32_e32 v57, v50
	v_mov_b32_e32 v58, v50
	v_mov_b32_e32 v59, v50
	v_mov_b32_e32 v60, v50
	v_mov_b32_e32 v61, v50
	v_mov_b32_e32 v62, v50
	v_mov_b32_e32 v63, v50
	v_mov_b32_e32 v64, v50
	v_mov_b32_e32 v65, v50
	s_mov_b32 s76, s53
	s_mov_b32 s53, s18
	v_add_u32_e32 v0, s53, v192
	v_exp_f32_e32 v82, v82
	v_exp_f32_e32 v195, v83
	v_exp_f32_e32 v84, v84
	v_exp_f32_e32 v196, v85
	v_exp_f32_e32 v83, v86
	v_exp_f32_e32 v85, v87
	v_exp_f32_e32 v86, v88
	v_exp_f32_e32 v87, v89
	s_waitcnt lgkmcnt(0)
	s_cmp_lg_u64 s[42:43], 0
	s_cbranch_scc0 .Lmy_y249
.LBB0_249:
	s_barrier
	ds_read_b128 v[34:37], v184 offset:0x3400
	ds_read_b128 v[38:41], v184 offset:0x4e00
	ds_read_b128 v[42:45], v184 offset:0x3420
	ds_read_b128 v[46:49], v184 offset:0x4e20
	ds_read_b128 v[170:173], v184 offset:0x3440
	ds_read_b128 v[174:177], v184 offset:0x4e40
	ds_read_b128 v[204:207], v184 offset:0x3460
	ds_read_b128 v[208:211], v184 offset:0x4e60
	s_waitcnt lgkmcnt(7)
	v_mfma_f32_32x32x16_bf16 v[114:129], v[34:37], v[150:153], v[50:65]
	v_exp_f32_e32 v88, v90
	v_exp_f32_e32 v89, v91
	v_exp_f32_e32 v90, v92
	v_exp_f32_e32 v91, v93
	s_waitcnt lgkmcnt(6)
	v_mfma_f32_32x32x16_bf16 v[98:113], v[38:41], v[150:153], v[50:65]
	v_exp_f32_e32 v92, v94
	v_exp_f32_e32 v93, v95
	v_exp_f32_e32 v94, v96
	v_exp_f32_e32 v95, v97
	s_waitcnt lgkmcnt(5)
	v_mfma_f32_32x32x16_bf16 v[114:129], v[42:45], v[146:149], v[114:129]
	v_cvt_pk_bf16_f32 v34, v82, v195
	v_cvt_pk_bf16_f32 v35, v84, v196
	v_cvt_pk_bf16_f32 v36, v83, v85
	v_cvt_pk_bf16_f32 v37, v86, v87
	s_waitcnt lgkmcnt(4)
	v_mfma_f32_32x32x16_bf16 v[98:113], v[46:49], v[146:149], v[98:113]
	v_exp_f32_e32 v96, v66
	v_exp_f32_e32 v97, v67
	v_exp_f32_e32 v197, v68
	v_exp_f32_e32 v198, v69
	ds_read_b128 v[38:41], v184 offset:0x3480
	ds_read_b128 v[66:69], v184 offset:0x4e80
	ds_read_b128 v[212:215], v184 offset:0x34a0
	ds_read_b128 v[216:219], v184 offset:0x4ea0
	s_waitcnt lgkmcnt(4)
	v_mfma_f32_32x32x16_bf16 v[114:129], v[170:173], v[142:145], v[114:129]
	v_exp_f32_e32 v199, v70
	v_exp_f32_e32 v200, v71
	v_exp_f32_e32 v201, v72
	v_exp_f32_e32 v202, v73
	v_mfma_f32_32x32x16_bf16 v[98:113], v[174:177], v[142:145], v[98:113]
	v_cvt_pk_bf16_f32 v42, v88, v89
	v_cvt_pk_bf16_f32 v43, v90, v91
	v_cvt_pk_bf16_f32 v44, v92, v93
	v_cvt_pk_bf16_f32 v45, v94, v95
	v_mfma_f32_32x32x16_bf16 v[114:129], v[204:207], v[138:141], v[114:129]
	v_exp_f32_e32 v203, v74
	v_exp_f32_e32 v204, v75
	v_exp_f32_e32 v205, v76
	v_exp_f32_e32 v206, v77
	v_mfma_f32_32x32x16_bf16 v[98:113], v[208:211], v[138:141], v[98:113]
	v_exp_f32_e32 v207, v78
	v_exp_f32_e32 v208, v79
	v_exp_f32_e32 v209, v80
	v_exp_f32_e32 v210, v81
	s_waitcnt lgkmcnt(0)
; template <int KB, bool HASY>
; __device__ __forceinline__ void phaseA(f32x16& X0, f32x16& X1, f32x16& Y0, f32x16& Y1, bf16x8& pa0, bf16x8& pa1, bf16x8& pa2, bf16x8& pa3,
;                                        const bf16x8* qr, const f32x16& negm, int kaddr, VFr& vf, int vb, float& l_reg) {
;     ...
;   X0 = MF(k8, qr[4], X0); if (HASY) { PACK8(Y1, 0, pa2); } SBAR();
;   X1 = MF(k9, qr[4], X1); if (HASY) { SUM4(Y1, 8); SUM4(Y1, 12); } SBAR();
;   X0 = MF(k10, qr[5], X0); if (HASY) { PACK8(Y1, 8, pa3); } SBAR();
;   X1 = MF(k11, qr[5], X1); if (HASY) vfr_issue<0>(vf, vb);
;   l_reg += ls;
;   SBAR();
; }
; template <bool HASX>
; __device__ __forceinline__ float phaseB(f32x16* o, bf16x8 pa0, bf16x8 pa1, bf16x8 pa2, bf16x8 pa3, VFr& f, int vb, const f32x16& X0, const f32x16& X1) {
;   SBAR(); VWAIT(f); VFr g; vfr_issue<2>(g, vb); SBAR();
;   float a = 0.f, b = 0.f;
;   o[0] = MF(pa0, PKV(f.a0, f.b0), o[0]); SBAR(); o[1] = MF(pa0, PKV(f.c0, f.d0), o[1]);
;   if (HASX) { a = MX3(X0[0], X0[1], X1[0]); b = MX3(X0[2], X0[3], X1[1]); a = MX3(a, X1[2], X1[3]); b = MX3(b, X0[4], X0[5]); } SBAR();
;   o[0] = MF(pa1, PKV(f.a1, f.b1), o[0]); if (HASX) { a = MX3(a, X0[6], X0[7]); b = MX3(b, X1[4], X1[5]); } SBAR();
;   o[1] = MF(pa1, PKV(f.c1, f.d1), o[1]); if (HASX) { a = MX3(a, X1[6], X1[7]); b = MX3(b, X0[8], X0[9]); a = MX3(a, X0[10], X0[11]); } SBAR();
;   VWAIT(g); SBAR();
;   o[0] = MF(pa2, PKV(g.a0, g.b0), o[0]); if (HASX) { b = MX3(b, X1[8], X1[9]); a = MX3(a, X1[10], X1[11]); } SBAR();
;   o[1] = MF(pa2, PKV(g.c0, g.d0), o[1]); if (HASX) { b = MX3(b, X0[12], X0[13]); a = MX3(a, X0[14], X0[15]); } SBAR();
;   o[0] = MF(pa3, PKV(g.a1, g.b1), o[0]); if (HASX) { b = MX3(b, X1[12], X1[13]); a = MX3(a, X1[14], X1[15]); } SBAR();
;   o[1] = MF(pa3, PKV(g.c1, g.d1), o[1]); SBAR();
;   float pmax = __builtin_fmaxf(a, b);
;   if (HASX) { auto rr = __builtin_amdgcn_permlane32_swap(__float_as_uint(pmax), __float_as_uint(pmax), false, false); pmax = __builtin_fmaxf(__uint_as_float(rr[0]), __uint_as_float(rr[1])); }
;   return pmax;
; }
; __device__ __forceinline__ void attn_unit(const bf16_t* __restrict__ Qb, const bf16_t* __restrict__ KNh, const bf16_t* __restrict__ KRb, const bf16_t* __restrict__ Vh,
;                                           bf16_t* __restrict__ Ob, int nkeys, char* lds, int tid_in) {
;     ...
;     SLOAD(SO, (j + 2) * KVBLK); SBAR();
	s_nop 0
	v_mfma_f32_32x32x16_bf16 v[114:129], v[38:41], v[134:137], v[114:129]
	v_cvt_pk_bf16_f32 v46, v96, v97
	v_cvt_pk_bf16_f32 v47, v197, v198
	v_cvt_pk_bf16_f32 v48, v199, v200
	v_cvt_pk_bf16_f32 v49, v201, v202
	v_mfma_f32_32x32x16_bf16 v[98:113], v[66:69], v[134:137], v[98:113]
	v_mfma_f32_32x32x16_bf16 v[114:129], v[212:215], v[130:133], v[114:129]
	v_cvt_pk_bf16_f32 v38, v203, v204
	v_cvt_pk_bf16_f32 v39, v205, v206
	v_cvt_pk_bf16_f32 v40, v207, v208
	v_cvt_pk_bf16_f32 v41, v209, v210
	ds_read_b64_tr_b16 v[78:79], v0 offset:0
	ds_read_b64_tr_b16 v[80:81], v0 offset:0x400
	ds_read_b64_tr_b16 v[74:75], v0 offset:0x200
	v_mfma_f32_32x32x16_bf16 v[98:113], v[216:219], v[130:133], v[98:113]
	ds_read_b64_tr_b16 v[76:77], v0 offset:0x600
	ds_read_b64_tr_b16 v[70:71], v0 offset:0x800
	ds_read_b64_tr_b16 v[72:73], v0 offset:0xc00
	ds_read_b64_tr_b16 v[66:67], v0 offset:0xa00
	ds_read_b64_tr_b16 v[68:69], v0 offset:0xe00
	s_add_i32 s18, s52, 0xffffe000
	buffer_load_dwordx4 v[170:173], v185, s[64:67], s18 offen
	buffer_load_dwordx4 v[174:177], v185, s[44:47], s18 offen
	s_add_i32 s28, s68, 0xfffff000
	buffer_load_dwordx4 v[158:161], v186, s[60:63], s28 offen
	s_waitcnt lgkmcnt(0)
	ds_read_b64_tr_b16 v[212:213], v0 offset:0x1000
	ds_read_b64_tr_b16 v[214:215], v0 offset:0x1400
	ds_read_b64_tr_b16 v[216:217], v0 offset:0x1200
	ds_read_b64_tr_b16 v[218:219], v0 offset:0x1600
	ds_read_b64_tr_b16 v[220:221], v0 offset:0x1800
	ds_read_b64_tr_b16 v[222:223], v0 offset:0x1c00
	ds_read_b64_tr_b16 v[228:229], v0 offset:0x1a00
	ds_read_b64_tr_b16 v[230:231], v0 offset:0x1e00
	v_mfma_f32_32x32x16_bf16 v[18:33], v[34:37], v[78:81], v[18:33]
	v_add_f32_e32 v238, v82, v195
	v_add_f32_e32 v239, v84, v196
	v_add_f32_e32 v240, v83, v85
	v_add_f32_e32 v241, v86, v87
	v_add_f32_e32 v238, v238, v239
	v_add_f32_e32 v240, v240, v241
	v_mfma_f32_32x32x16_bf16 v[2:17], v[34:37], v[74:77], v[2:17]
	v_max_f32_e32 v34, v114, v115
	v_max3_f32 v35, v116, v117, v99
	v_max3_f32 v34, v34, v98, v100
	v_max3_f32 v35, v35, v118, v119
	v_mfma_f32_32x32x16_bf16 v[18:33], v[42:45], v[70:73], v[18:33]
	v_max3_f32 v34, v34, v101, v120
	v_max3_f32 v35, v35, v102, v103
	v_add_f32_e32 v238, v240, v238
	v_add_f32_e32 v239, v88, v89
	v_add_f32_e32 v241, v90, v91
	v_mfma_f32_32x32x16_bf16 v[2:17], v[42:45], v[66:69], v[2:17]
	v_max3_f32 v34, v34, v121, v104
	v_max3_f32 v34, v34, v105, v124
	v_max3_f32 v35, v35, v122, v123
	v_add_f32_e32 v239, v239, v241
	v_add_f32_e32 v240, v92, v93
	v_add_f32_e32 v241, v94, v95
	s_waitcnt lgkmcnt(0)
	v_mfma_f32_32x32x16_bf16 v[18:33], v[46:49], v[212:215], v[18:33]
	v_max3_f32 v34, v34, v125, v108
	v_max3_f32 v35, v35, v106, v107
	v_add_f32_e32 v238, v239, v238
	v_add_f32_e32 v240, v240, v241
	s_waitcnt vmcnt(3)
	v_add_u32_e32 v67, s69, v187
	ds_write_b128 v67, v[162:165]
	v_mfma_f32_32x32x16_bf16 v[2:17], v[46:49], v[216:219], v[2:17]
	v_max3_f32 v34, v34, v109, v128
	v_max3_f32 v35, v35, v126, v127
	v_add_f32_e32 v238, v240, v238
	v_add_f32_e32 v239, v96, v97
	v_add_f32_e32 v241, v197, v198
	s_waitcnt vmcnt(2)
	ds_write_b128 v188, v[166:169] offset:24576
	v_mfma_f32_32x32x16_bf16 v[18:33], v[38:41], v[220:223], v[18:33]
	v_max3_f32 v34, v34, v129, v112
	v_max3_f32 v35, v35, v110, v111
	v_add_f32_e32 v239, v239, v241
	v_add_f32_e32 v240, v199, v200
	v_add_f32_e32 v241, v201, v202
	ds_write_b128 v193, v[154:157] offset:24704
	v_add_f32_e32 v238, v239, v238
	v_add_f32_e32 v240, v240, v241
	v_mfma_f32_32x32x16_bf16 v[2:17], v[38:41], v[228:231], v[2:17]
	v_max3_f32 v34, v34, v113, v35
	v_cmp_lt_f32_e32 vcc, s35, v34
	v_add_f32_e32 v238, v240, v238
	v_add_f32_e32 v239, v203, v204
	v_add_f32_e32 v241, v205, v206
	v_add_f32_e32 v239, v239, v241
	v_add_f32_e32 v240, v207, v208
	v_add_f32_e32 v241, v209, v210
	v_add_f32_e32 v238, v239, v238
	v_add_f32_e32 v240, v240, v241
	v_add_f32_e32 v238, v240, v238
	v_add_f32_e32 v194, v194, v238
	s_cbranch_vccnz .LBB0_272
; #define SBAR() __builtin_amdgcn_sched_barrier(0)
; template <int KB, bool HASY>
; __device__ __forceinline__ void phaseA(f32x16& X0, f32x16& X1, f32x16& Y0, f32x16& Y1, bf16x8& pa0, bf16x8& pa1, bf16x8& pa2, bf16x8& pa3,
;                                        const bf16x8* qr, const f32x16& negm, int kaddr, VFr& vf, int vb, float& l_reg) {
;   SBAR();
;   float ls = 0.f;
;   bf16x8 k0 = rd128<KOFF(KB, 0, 0)>(kaddr), k1 = rd128<KOFF(KB, 1, 0)>(kaddr), k2 = rd128<KOFF(KB, 0, 1)>(kaddr), k3 = rd128<KOFF(KB, 1, 1)>(kaddr);
;   if (HASY) { EXP4(Y0, 0); EXP4(Y0, 4); }
;   SBAR(); WAIT4(k0, k1, k2, k3);
;   bf16x8 k4 = rd128<KOFF(KB, 0, 2)>(kaddr), k5 = rd128<KOFF(KB, 1, 2)>(kaddr), k6 = rd128<KOFF(KB, 0, 3)>(kaddr), k7 = rd128<KOFF(KB, 1, 3)>(kaddr);
;   SBAR();
;   X0 = MF(k0, qr[0], negm); if (HASY) { EXP4(Y0, 8); SUM4(Y0, 0); } SBAR();
;   X1 = MF(k1, qr[0], negm); if (HASY) { EXP4(Y0, 12); SUM4(Y0, 4); } SBAR();
;   X0 = MF(k2, qr[1], X0); if (HASY) { PACK8(Y0, 0, pa0); } SBAR();
;   X1 = MF(k3, qr[1], X1); if (HASY) { EXP4(Y1, 0); SUM4(Y0, 8); } SBAR();
;   WAIT4(k4, k5, k6, k7);
;   bf16x8 k8 = rd128<KOFF(KB, 0, 4)>(kaddr), k9 = rd128<KOFF(KB, 1, 4)>(kaddr), k10 = rd128<KOFF(KB, 0, 5)>(kaddr), k11 = rd128<KOFF(KB, 1, 5)>(kaddr);
;   SBAR();
;   X0 = MF(k4, qr[2], X0); if (HASY) { EXP4(Y1, 4); SUM4(Y0, 12); } SBAR();
;   X1 = MF(k5, qr[2], X1); if (HASY) { PACK8(Y0, 8, pa1); } SBAR();
;   X0 = MF(k6, qr[3], X0); if (HASY) { EXP4(Y1, 8); SUM4(Y1, 0); } SBAR();
;   X1 = MF(k7, qr[3], X1); if (HASY) { EXP4(Y1, 12); SUM4(Y1, 4); } SBAR();
;   WAIT4(k8, k9, k10, k11);
;   SBAR();
;   X0 = MF(k8, qr[4], X0); if (HASY) { PACK8(Y1, 0, pa2); } SBAR();
;   X1 = MF(k9, qr[4], X1); if (HASY) { SUM4(Y1, 8); SUM4(Y1, 12); } SBAR();
;   X0 = MF(k10, qr[5], X0); if (HASY) { PACK8(Y1, 8, pa3); } SBAR();
;   X1 = MF(k11, qr[5], X1); if (HASY) vfr_issue<0>(vf, vb);
; __device__ __forceinline__ void attn_unit(const bf16_t* __restrict__ Qb, const bf16_t* __restrict__ KNh, const bf16_t* __restrict__ KRb, const bf16_t* __restrict__ Vh,
;                                           bf16_t* __restrict__ Ob, int nkeys, char* lds, int tid_in) {
;     ...
;     RESC(alB); __syncthreads(); ROT();
;     phaseA<0, true>(pA0, pA1, pB0, pB1, pa0, pa1, pa2, pa3, qr, negm, kaddr, vf, vb0 + vprev, l_reg);
;     if (j + 3 < NT) SLOAD(SE, (j + 3) * KVBLK); SBAR();
.LBB0_259:
	v_add_u32_e32 v237, s76, v192
	v_exp_f32_e32 v195, v114
	v_exp_f32_e32 v197, v115
	v_exp_f32_e32 v198, v116
	v_exp_f32_e32 v201, v117
	v_exp_f32_e32 v196, v118
	v_exp_f32_e32 v199, v119
	v_exp_f32_e32 v200, v120
	v_exp_f32_e32 v202, v121
	s_waitcnt lgkmcnt(0)
	s_barrier
	ds_read_b128 v[66:69], v184 offset:0
	ds_read_b128 v[212:215], v184 offset:0x1a00
	ds_read_b128 v[216:219], v184 offset:32
	ds_read_b128 v[118:121], v184 offset:0x1a20
	ds_read_b128 v[220:223], v184 offset:64
	ds_read_b128 v[228:231], v184 offset:0x1a40
	ds_read_b128 v[238:241], v184 offset:0x60
	ds_read_b128 v[242:245], v184 offset:0x1a60
	s_waitcnt lgkmcnt(7)
	v_mfma_f32_32x32x16_bf16 v[82:97], v[66:69], v[150:153], v[50:65]
	v_exp_f32_e32 v203, v122
	v_exp_f32_e32 v204, v123
	v_exp_f32_e32 v205, v124
	v_exp_f32_e32 v206, v125
	s_waitcnt lgkmcnt(6)
	v_mfma_f32_32x32x16_bf16 v[66:81], v[212:215], v[150:153], v[50:65]
	v_exp_f32_e32 v207, v126
	v_exp_f32_e32 v208, v127
	v_exp_f32_e32 v209, v128
	v_exp_f32_e32 v210, v129
	s_waitcnt lgkmcnt(5)
	v_mfma_f32_32x32x16_bf16 v[82:97], v[216:219], v[146:149], v[82:97]
	v_cvt_pk_bf16_f32 v114, v195, v197
	v_cvt_pk_bf16_f32 v115, v198, v201
	v_cvt_pk_bf16_f32 v116, v196, v199
	v_cvt_pk_bf16_f32 v117, v200, v202
	s_waitcnt lgkmcnt(4)
	v_mfma_f32_32x32x16_bf16 v[66:81], v[118:121], v[146:149], v[66:81]
	v_exp_f32_e32 v211, v98
	v_exp_f32_e32 v212, v99
	v_exp_f32_e32 v213, v100
	v_exp_f32_e32 v214, v101
	ds_read_b128 v[98:101], v184 offset:0x80
	ds_read_b128 v[118:121], v184 offset:0x1a80
	ds_read_b128 v[122:125], v184 offset:0xa0
	ds_read_b128 v[246:249], v184 offset:0x1aa0
	s_waitcnt lgkmcnt(4)
	v_mfma_f32_32x32x16_bf16 v[82:97], v[220:223], v[142:145], v[82:97]
	v_exp_f32_e32 v215, v102
	v_exp_f32_e32 v216, v103
	v_exp_f32_e32 v217, v104
	v_exp_f32_e32 v218, v105
	v_mfma_f32_32x32x16_bf16 v[66:81], v[228:231], v[142:145], v[66:81]
	v_cvt_pk_bf16_f32 v102, v203, v204
	v_cvt_pk_bf16_f32 v103, v205, v206
	v_cvt_pk_bf16_f32 v104, v207, v208
	v_cvt_pk_bf16_f32 v105, v209, v210
	v_mfma_f32_32x32x16_bf16 v[82:97], v[238:241], v[138:141], v[82:97]
	v_exp_f32_e32 v219, v106
	v_exp_f32_e32 v220, v107
	v_exp_f32_e32 v221, v108
	v_exp_f32_e32 v222, v109
	v_mfma_f32_32x32x16_bf16 v[66:81], v[242:245], v[138:141], v[66:81]
	v_exp_f32_e32 v223, v110
	v_exp_f32_e32 v234, v111
	v_exp_f32_e32 v235, v112
	v_exp_f32_e32 v236, v113
	s_waitcnt lgkmcnt(0)
	s_nop 0
	v_mfma_f32_32x32x16_bf16 v[82:97], v[98:101], v[134:137], v[82:97]
	v_cvt_pk_bf16_f32 v106, v211, v212
	v_cvt_pk_bf16_f32 v107, v213, v214
	v_cvt_pk_bf16_f32 v108, v215, v216
	v_cvt_pk_bf16_f32 v109, v217, v218
	v_mfma_f32_32x32x16_bf16 v[66:81], v[118:121], v[134:137], v[66:81]
	v_mfma_f32_32x32x16_bf16 v[82:97], v[122:125], v[130:133], v[82:97]
	v_cvt_pk_bf16_f32 v98, v219, v220
	v_cvt_pk_bf16_f32 v99, v221, v222
	v_cvt_pk_bf16_f32 v100, v223, v234
	v_cvt_pk_bf16_f32 v101, v235, v236
	ds_read_b64_tr_b16 v[126:127], v237 offset:0
	ds_read_b64_tr_b16 v[128:129], v237 offset:0x400
	ds_read_b64_tr_b16 v[122:123], v237 offset:0x200
	v_mfma_f32_32x32x16_bf16 v[66:81], v[246:249], v[130:133], v[66:81]
	ds_read_b64_tr_b16 v[124:125], v237 offset:0x600
	ds_read_b64_tr_b16 v[118:119], v237 offset:0x800
	ds_read_b64_tr_b16 v[120:121], v237 offset:0xc00
	ds_read_b64_tr_b16 v[110:111], v237 offset:0xa00
	ds_read_b64_tr_b16 v[112:113], v237 offset:0xe00
	s_cmp_ge_u32 s39, s38
	s_cselect_b64 s[18:19], -1, 0
	s_and_b64 vcc, exec, s[18:19]
	s_cbranch_vccnz .LBB0_263
	buffer_load_dwordx4 v[162:165], v185, s[64:67], s52 offen
	buffer_load_dwordx4 v[166:169], v185, s[44:47], s52 offen
	buffer_load_dwordx4 v[154:157], v186, s[60:63], s68 offen

; #define SBAR() __builtin_amdgcn_sched_barrier(0)
; #define EXP4(P, B) do { P[B] = __builtin_amdgcn_exp2f(P[B]); P[B + 1] = __builtin_amdgcn_exp2f(P[B + 1]); P[B + 2] = __builtin_amdgcn_exp2f(P[B + 2]); P[B + 3] = __builtin_amdgcn_exp2f(P[B + 3]); } while (0)
; #define SLOAD(i, k0) do { sr_[i].vs = BLD(rV, goff_kv, (k0) * 128); sr_[i].ks = BLD(rK, goff_kv, (k0) * 128); if (krt) sr_[i].kr = BLD(rR, goff_kr, (k0) * 64); } while (0)
; #define SWRITE(b, voff, i) do { *(bf16x8*)(V_lds + (voff) + vst0) = sr_[i].vs; *(bf16x8*)(K_lds + (b) * SHM_K + kst0) = sr_[i].ks; \
;     if (krt) *(bf16x8*)(K_lds + (b) * SHM_K + kst1) = sr_[i].kr; } while (0)
; #define SWAIT() do { asm volatile("s_waitcnt vmcnt(3)" ::: "memory"); } while (0)
; #define RESC(a) do { if (__any((a) < 1.f)) { if (hi == 0) al_l[r32] = (a); asm volatile("s_waitcnt lgkmcnt(0)" ::: "memory"); l_reg *= (a); \
;     _Pragma("unroll") for (int d = 0; d < 2; ++d) _Pragma("unroll") for (int r = 0; r < 16; ++r) o[d][r] *= al_l[crow(r, hi)]; } } while (0)
; template <int KB, bool HASY>
; __device__ __forceinline__ void phaseA(f32x16& X0, f32x16& X1, f32x16& Y0, f32x16& Y1, bf16x8& pa0, bf16x8& pa1, bf16x8& pa2, bf16x8& pa3,
;                                        const bf16x8* qr, const f32x16& negm, int kaddr, VFr& vf, int vb, float& l_reg) {
;     ...
;   if (HASY) { EXP4(Y0, 0); EXP4(Y0, 4); }
; __device__ __forceinline__ void attn_unit(const bf16_t* __restrict__ Qb, const bf16_t* __restrict__ KNh, const bf16_t* __restrict__ KRb, const bf16_t* __restrict__ Vh,
;                                           bf16_t* __restrict__ Ob, int nkeys, char* lds, int tid_in) {
;     ...
;   for (int j = 1; j + 1 < NT; j += 2) {
;     phaseA<1, true>(pB0, pB1, pA0, pA1, pa0, pa1, pa2, pa3, qr, negm, kaddr, vf, vb0 + vprev, l_reg);
;     SLOAD(SO, (j + 2) * KVBLK); SBAR();
;     alB = decide<false>(phaseB<true>(o, pa0, pa1, pa2, pa3, vf, vb0 + vprev, pB0, pB1), pB0, pB1, m_reg, negm);
;     SWAIT(); SWRITE(0, vnext, SE);
;     RESC(alB); __syncthreads(); ROT();
;     phaseA<0, true>(pA0, pA1, pB0, pB1, pa0, pa1, pa2, pa3, qr, negm, kaddr, vf, vb0 + vprev, l_reg);
;     if (j + 3 < NT) SLOAD(SE, (j + 3) * KVBLK); SBAR();
;     alA = decide<false>(phaseB<true>(o, pa0, pa1, pa2, pa3, vf, vb0 + vprev, pA0, pA1), pA0, pA1, m_reg, negm);
;     SWAIT(); SWRITE(1, vnext, SO);
;     RESC(alA); __syncthreads(); ROT();
;   }
.LBB0_270:
	s_addk_i32 s52, 0x4000
	s_addk_i32 s68, 0x2000
	s_add_i32 s39, s39, 2
	s_and_b64 vcc, exec, s[18:19]
	s_cbranch_vccnz .Lmy_xexit
	s_mov_b32 s18, s69
	s_mov_b32 s69, s76
	s_mov_b32 s76, s53
	s_mov_b32 s53, s18
	v_add_u32_e32 v0, s53, v192
	v_exp_f32_e32 v82, v82
	v_exp_f32_e32 v195, v83
	v_exp_f32_e32 v84, v84
	v_exp_f32_e32 v196, v85
	v_exp_f32_e32 v83, v86
	v_exp_f32_e32 v85, v87
	v_exp_f32_e32 v86, v88
	v_exp_f32_e32 v87, v89
	s_waitcnt lgkmcnt(0)
	s_branch .LBB0_249
.Lmy_xexit:
	s_waitcnt lgkmcnt(0)
	s_barrier
	s_branch .LBB0_274

; template <int KB, bool HASY>
; __device__ __forceinline__ void phaseA(f32x16& X0, f32x16& X1, f32x16& Y0, f32x16& Y1, bf16x8& pa0, bf16x8& pa1, bf16x8& pa2, bf16x8& pa3,
;                                        const bf16x8* qr, const f32x16& negm, int kaddr, VFr& vf, int vb, float& l_reg) {
;   SBAR();
;   float ls = 0.f;
;   bf16x8 k0 = rd128<KOFF(KB, 0, 0)>(kaddr), k1 = rd128<KOFF(KB, 1, 0)>(kaddr), k2 = rd128<KOFF(KB, 0, 1)>(kaddr), k3 = rd128<KOFF(KB, 1, 1)>(kaddr);
;   if (HASY) { EXP4(Y0, 0); EXP4(Y0, 4); }
;   SBAR(); WAIT4(k0, k1, k2, k3);
;   bf16x8 k4 = rd128<KOFF(KB, 0, 2)>(kaddr), k5 = rd128<KOFF(KB, 1, 2)>(kaddr), k6 = rd128<KOFF(KB, 0, 3)>(kaddr), k7 = rd128<KOFF(KB, 1, 3)>(kaddr);
;   SBAR();
;   X0 = MF(k0, qr[0], negm); if (HASY) { EXP4(Y0, 8); SUM4(Y0, 0); } SBAR();
;   X1 = MF(k1, qr[0], negm); if (HASY) { EXP4(Y0, 12); SUM4(Y0, 4); } SBAR();
;   X0 = MF(k2, qr[1], X0); if (HASY) { PACK8(Y0, 0, pa0); } SBAR();
;   X1 = MF(k3, qr[1], X1); if (HASY) { EXP4(Y1, 0); SUM4(Y0, 8); } SBAR();
;   WAIT4(k4, k5, k6, k7);
;   bf16x8 k8 = rd128<KOFF(KB, 0, 4)>(kaddr), k9 = rd128<KOFF(KB, 1, 4)>(kaddr), k10 = rd128<KOFF(KB, 0, 5)>(kaddr), k11 = rd128<KOFF(KB, 1, 5)>(kaddr);
;   SBAR();
;   X0 = MF(k4, qr[2], X0); if (HASY) { EXP4(Y1, 4); SUM4(Y0, 12); } SBAR();
;   X1 = MF(k5, qr[2], X1); if (HASY) { PACK8(Y0, 8, pa1); } SBAR();
;   X0 = MF(k6, qr[3], X0); if (HASY) { EXP4(Y1, 8); SUM4(Y1, 0); } SBAR();
;   X1 = MF(k7, qr[3], X1); if (HASY) { EXP4(Y1, 12); SUM4(Y1, 4); } SBAR();
;   WAIT4(k8, k9, k10, k11);
;   SBAR();
;   X0 = MF(k8, qr[4], X0); if (HASY) { PACK8(Y1, 0, pa2); } SBAR();
;   X1 = MF(k9, qr[4], X1); if (HASY) { SUM4(Y1, 8); SUM4(Y1, 12); } SBAR();
;   X0 = MF(k10, qr[5], X0); if (HASY) { PACK8(Y1, 8, pa3); } SBAR();
;   X1 = MF(k11, qr[5], X1); if (HASY) vfr_issue<0>(vf, vb);
;   l_reg += ls;
;   SBAR();
; }
; template <bool HASX>
; __device__ __forceinline__ float phaseB(f32x16* o, bf16x8 pa0, bf16x8 pa1, bf16x8 pa2, bf16x8 pa3, VFr& f, int vb, const f32x16& X0, const f32x16& X1) {
;   SBAR(); VWAIT(f); VFr g; vfr_issue<2>(g, vb); SBAR();
;   float a = 0.f, b = 0.f;
;   o[0] = MF(pa0, PKV(f.a0, f.b0), o[0]); SBAR(); o[1] = MF(pa0, PKV(f.c0, f.d0), o[1]);
;   if (HASX) { a = MX3(X0[0], X0[1], X1[0]); b = MX3(X0[2], X0[3], X1[1]); a = MX3(a, X1[2], X1[3]); b = MX3(b, X0[4], X0[5]); } SBAR();
.Lmy_y249:
	s_barrier
	ds_read_b128 v[34:37], v184 offset:0x3400
	ds_read_b128 v[38:41], v184 offset:0x4e00
	ds_read_b128 v[42:45], v184 offset:0x3420
	ds_read_b128 v[46:49], v184 offset:0x4e20
	ds_read_b128 v[170:173], v184 offset:0x3440
	ds_read_b128 v[174:177], v184 offset:0x4e40
	ds_read_b128 v[204:207], v184 offset:0x3460
	ds_read_b128 v[208:211], v184 offset:0x4e60
	s_waitcnt lgkmcnt(7)
	v_mfma_f32_32x32x16_bf16 v[114:129], v[34:37], v[150:153], v[50:65]
	v_exp_f32_e32 v88, v90
	v_exp_f32_e32 v89, v91
	v_exp_f32_e32 v90, v92
	v_exp_f32_e32 v91, v93
	s_waitcnt lgkmcnt(6)
	v_mfma_f32_32x32x16_bf16 v[98:113], v[38:41], v[150:153], v[50:65]
	v_exp_f32_e32 v92, v94
	v_exp_f32_e32 v93, v95
	v_exp_f32_e32 v94, v96
	v_exp_f32_e32 v95, v97
	s_waitcnt lgkmcnt(5)
	v_mfma_f32_32x32x16_bf16 v[114:129], v[42:45], v[146:149], v[114:129]
	v_cvt_pk_bf16_f32 v34, v82, v195
	v_cvt_pk_bf16_f32 v35, v84, v196
	v_cvt_pk_bf16_f32 v36, v83, v85
	v_cvt_pk_bf16_f32 v37, v86, v87
	s_waitcnt lgkmcnt(4)
	v_mfma_f32_32x32x16_bf16 v[98:113], v[46:49], v[146:149], v[98:113]
	v_exp_f32_e32 v96, v66
	v_exp_f32_e32 v97, v67
	v_exp_f32_e32 v197, v68
	v_exp_f32_e32 v198, v69
	ds_read_b128 v[38:41], v184 offset:0x3480
	ds_read_b128 v[66:69], v184 offset:0x4e80
	ds_read_b128 v[212:215], v184 offset:0x34a0
	ds_read_b128 v[216:219], v184 offset:0x4ea0
	s_waitcnt lgkmcnt(4)
	v_mfma_f32_32x32x16_bf16 v[114:129], v[170:173], v[142:145], v[114:129]
	v_exp_f32_e32 v199, v70
	v_exp_f32_e32 v200, v71
	v_exp_f32_e32 v201, v72
	v_exp_f32_e32 v202, v73
	v_mfma_f32_32x32x16_bf16 v[98:113], v[174:177], v[142:145], v[98:113]
	v_cvt_pk_bf16_f32 v42, v88, v89
	v_cvt_pk_bf16_f32 v43, v90, v91
	v_cvt_pk_bf16_f32 v44, v92, v93
	v_cvt_pk_bf16_f32 v45, v94, v95
	v_mfma_f32_32x32x16_bf16 v[114:129], v[204:207], v[138:141], v[114:129]
	v_exp_f32_e32 v203, v74
	v_exp_f32_e32 v204, v75
	v_exp_f32_e32 v205, v76
	v_exp_f32_e32 v206, v77
	v_mfma_f32_32x32x16_bf16 v[98:113], v[208:211], v[138:141], v[98:113]
	v_exp_f32_e32 v207, v78
	v_exp_f32_e32 v208, v79
	v_exp_f32_e32 v209, v80
	v_exp_f32_e32 v210, v81
	s_waitcnt lgkmcnt(0)
	s_nop 0
	v_mfma_f32_32x32x16_bf16 v[114:129], v[38:41], v[134:137], v[114:129]
	v_cvt_pk_bf16_f32 v46, v96, v97
	v_cvt_pk_bf16_f32 v47, v197, v198
	v_cvt_pk_bf16_f32 v48, v199, v200
	v_cvt_pk_bf16_f32 v49, v201, v202
	v_mfma_f32_32x32x16_bf16 v[98:113], v[66:69], v[134:137], v[98:113]
	v_mfma_f32_32x32x16_bf16 v[114:129], v[212:215], v[130:133], v[114:129]
	v_cvt_pk_bf16_f32 v38, v203, v204
	v_cvt_pk_bf16_f32 v39, v205, v206
	v_cvt_pk_bf16_f32 v40, v207, v208
	v_cvt_pk_bf16_f32 v41, v209, v210
	ds_read_b64_tr_b16 v[78:79], v0 offset:0
	ds_read_b64_tr_b16 v[80:81], v0 offset:0x400
	ds_read_b64_tr_b16 v[74:75], v0 offset:0x200
	v_mfma_f32_32x32x16_bf16 v[98:113], v[216:219], v[130:133], v[98:113]
	ds_read_b64_tr_b16 v[76:77], v0 offset:0x600
	ds_read_b64_tr_b16 v[70:71], v0 offset:0x800
	ds_read_b64_tr_b16 v[72:73], v0 offset:0xc00
	ds_read_b64_tr_b16 v[66:67], v0 offset:0xa00
	ds_read_b64_tr_b16 v[68:69], v0 offset:0xe00
	s_add_i32 s18, s52, 0xffffe000
	buffer_load_dwordx4 v[170:173], v185, s[64:67], s18 offen
	buffer_load_dwordx4 v[174:177], v185, s[44:47], s18 offen
	s_waitcnt lgkmcnt(0)
	ds_read_b64_tr_b16 v[212:213], v0 offset:0x1000
	ds_read_b64_tr_b16 v[214:215], v0 offset:0x1400
	ds_read_b64_tr_b16 v[216:217], v0 offset:0x1200
	ds_read_b64_tr_b16 v[218:219], v0 offset:0x1600
	ds_read_b64_tr_b16 v[220:221], v0 offset:0x1800
	ds_read_b64_tr_b16 v[222:223], v0 offset:0x1c00
	ds_read_b64_tr_b16 v[228:229], v0 offset:0x1a00
	ds_read_b64_tr_b16 v[230:231], v0 offset:0x1e00
	v_mfma_f32_32x32x16_bf16 v[18:33], v[34:37], v[78:81], v[18:33]
	v_add_f32_e32 v238, v82, v195
	v_add_f32_e32 v239, v84, v196
	v_add_f32_e32 v240, v83, v85
	v_add_f32_e32 v241, v86, v87
	v_add_f32_e32 v238, v238, v239
	v_add_f32_e32 v240, v240, v241
	v_mfma_f32_32x32x16_bf16 v[2:17], v[34:37], v[74:77], v[2:17]
	v_max_f32_e32 v34, v114, v115
	v_max3_f32 v35, v116, v117, v99
	v_max3_f32 v34, v34, v98, v100
	v_max3_f32 v35, v35, v118, v119
	v_mfma_f32_32x32x16_bf16 v[18:33], v[42:45], v[70:73], v[18:33]
	v_max3_f32 v34, v34, v101, v120
	v_max3_f32 v35, v35, v102, v103
	v_add_f32_e32 v238, v240, v238
	v_add_f32_e32 v239, v88, v89
	v_add_f32_e32 v241, v90, v91
	v_mfma_f32_32x32x16_bf16 v[2:17], v[42:45], v[66:69], v[2:17]
	v_max3_f32 v34, v34, v121, v104
	v_max3_f32 v34, v34, v105, v124
	v_max3_f32 v35, v35, v122, v123
	v_add_f32_e32 v239, v239, v241
	v_add_f32_e32 v240, v92, v93
	v_add_f32_e32 v241, v94, v95
	s_waitcnt lgkmcnt(0)
	v_mfma_f32_32x32x16_bf16 v[18:33], v[46:49], v[212:215], v[18:33]
	v_max3_f32 v34, v34, v125, v108
	v_max3_f32 v35, v35, v106, v107
	v_add_f32_e32 v238, v239, v238
	v_add_f32_e32 v240, v240, v241
	s_waitcnt vmcnt(3)
	v_add_u32_e32 v67, s69, v187
	ds_write_b128 v67, v[162:165]
	v_mfma_f32_32x32x16_bf16 v[2:17], v[46:49], v[216:219], v[2:17]
	v_max3_f32 v34, v34, v109, v128
	v_max3_f32 v35, v35, v126, v127
	v_add_f32_e32 v238, v240, v238
	v_add_f32_e32 v239, v96, v97
	v_add_f32_e32 v241, v197, v198
	s_waitcnt vmcnt(2)
	ds_write_b128 v188, v[166:169] offset:24576
	v_mfma_f32_32x32x16_bf16 v[18:33], v[38:41], v[220:223], v[18:33]
	v_max3_f32 v34, v34, v129, v112
	v_max3_f32 v35, v35, v110, v111
	v_add_f32_e32 v239, v239, v241
	v_add_f32_e32 v240, v199, v200
	v_add_f32_e32 v241, v201, v202
	v_add_f32_e32 v238, v239, v238
	v_add_f32_e32 v240, v240, v241
	v_mfma_f32_32x32x16_bf16 v[2:17], v[38:41], v[228:231], v[2:17]
	v_max3_f32 v34, v34, v113, v35
	v_cmp_lt_f32_e32 vcc, s35, v34
	v_add_f32_e32 v238, v240, v238
	v_add_f32_e32 v239, v203, v204
	v_add_f32_e32 v241, v205, v206
	v_add_f32_e32 v239, v239, v241
	v_add_f32_e32 v240, v207, v208
	v_add_f32_e32 v241, v209, v210
	v_add_f32_e32 v238, v239, v238
	v_add_f32_e32 v240, v240, v241
	v_add_f32_e32 v238, v240, v238
	v_add_f32_e32 v194, v194, v238
	s_cbranch_vccnz .Lmy_y272
; #define SBAR() __builtin_amdgcn_sched_barrier(0)
; template <int KB, bool HASY>
; __device__ __forceinline__ void phaseA(f32x16& X0, f32x16& X1, f32x16& Y0, f32x16& Y1, bf16x8& pa0, bf16x8& pa1, bf16x8& pa2, bf16x8& pa3,
;                                        const bf16x8* qr, const f32x16& negm, int kaddr, VFr& vf, int vb, float& l_reg) {
;   SBAR();
;   float ls = 0.f;
;   bf16x8 k0 = rd128<KOFF(KB, 0, 0)>(kaddr), k1 = rd128<KOFF(KB, 1, 0)>(kaddr), k2 = rd128<KOFF(KB, 0, 1)>(kaddr), k3 = rd128<KOFF(KB, 1, 1)>(kaddr);
;   if (HASY) { EXP4(Y0, 0); EXP4(Y0, 4); }
;   SBAR(); WAIT4(k0, k1, k2, k3);
;   bf16x8 k4 = rd128<KOFF(KB, 0, 2)>(kaddr), k5 = rd128<KOFF(KB, 1, 2)>(kaddr), k6 = rd128<KOFF(KB, 0, 3)>(kaddr), k7 = rd128<KOFF(KB, 1, 3)>(kaddr);
;   SBAR();
;   X0 = MF(k0, qr[0], negm); if (HASY) { EXP4(Y0, 8); SUM4(Y0, 0); } SBAR();
;   X1 = MF(k1, qr[0], negm); if (HASY) { EXP4(Y0, 12); SUM4(Y0, 4); } SBAR();
;   X0 = MF(k2, qr[1], X0); if (HASY) { PACK8(Y0, 0, pa0); } SBAR();
;   X1 = MF(k3, qr[1], X1); if (HASY) { EXP4(Y1, 0); SUM4(Y0, 8); } SBAR();
;   WAIT4(k4, k5, k6, k7);
;   bf16x8 k8 = rd128<KOFF(KB, 0, 4)>(kaddr), k9 = rd128<KOFF(KB, 1, 4)>(kaddr), k10 = rd128<KOFF(KB, 0, 5)>(kaddr), k11 = rd128<KOFF(KB, 1, 5)>(kaddr);
;   SBAR();
;   X0 = MF(k4, qr[2], X0); if (HASY) { EXP4(Y1, 4); SUM4(Y0, 12); } SBAR();
;   X1 = MF(k5, qr[2], X1); if (HASY) { PACK8(Y0, 8, pa1); } SBAR();
;   X0 = MF(k6, qr[3], X0); if (HASY) { EXP4(Y1, 8); SUM4(Y1, 0); } SBAR();
;   X1 = MF(k7, qr[3], X1); if (HASY) { EXP4(Y1, 12); SUM4(Y1, 4); } SBAR();
;   WAIT4(k8, k9, k10, k11);
;   SBAR();
;   X0 = MF(k8, qr[4], X0); if (HASY) { PACK8(Y1, 0, pa2); } SBAR();
;   X1 = MF(k9, qr[4], X1); if (HASY) { SUM4(Y1, 8); SUM4(Y1, 12); } SBAR();
;   X0 = MF(k10, qr[5], X0); if (HASY) { PACK8(Y1, 8, pa3); } SBAR();
;   X1 = MF(k11, qr[5], X1); if (HASY) vfr_issue<0>(vf, vb);
; __device__ __forceinline__ void attn_unit(const bf16_t* __restrict__ Qb, const bf16_t* __restrict__ KNh, const bf16_t* __restrict__ KRb, const bf16_t* __restrict__ Vh,
;                                           bf16_t* __restrict__ Ob, int nkeys, char* lds, int tid_in) {
;     ...
;     RESC(alB); __syncthreads(); ROT();
;     phaseA<0, true>(pA0, pA1, pB0, pB1, pa0, pa1, pa2, pa3, qr, negm, kaddr, vf, vb0 + vprev, l_reg);
;     if (j + 3 < NT) SLOAD(SE, (j + 3) * KVBLK); SBAR();
.Lmy_y259:
	v_add_u32_e32 v237, s76, v192
	v_exp_f32_e32 v195, v114
	v_exp_f32_e32 v197, v115
	v_exp_f32_e32 v198, v116
	v_exp_f32_e32 v201, v117
	v_exp_f32_e32 v196, v118
	v_exp_f32_e32 v199, v119
	v_exp_f32_e32 v200, v120
	v_exp_f32_e32 v202, v121
	s_waitcnt lgkmcnt(0)
	s_barrier
	ds_read_b128 v[66:69], v184 offset:0
	ds_read_b128 v[212:215], v184 offset:0x1a00
	ds_read_b128 v[216:219], v184 offset:32
	ds_read_b128 v[118:121], v184 offset:0x1a20
	ds_read_b128 v[220:223], v184 offset:64
	ds_read_b128 v[228:231], v184 offset:0x1a40
	ds_read_b128 v[238:241], v184 offset:0x60
	ds_read_b128 v[242:245], v184 offset:0x1a60
	s_waitcnt lgkmcnt(7)
	v_mfma_f32_32x32x16_bf16 v[82:97], v[66:69], v[150:153], v[50:65]
	v_exp_f32_e32 v203, v122
	v_exp_f32_e32 v204, v123
	v_exp_f32_e32 v205, v124
	v_exp_f32_e32 v206, v125
	s_waitcnt lgkmcnt(6)
	v_mfma_f32_32x32x16_bf16 v[66:81], v[212:215], v[150:153], v[50:65]
	v_exp_f32_e32 v207, v126
	v_exp_f32_e32 v208, v127
	v_exp_f32_e32 v209, v128
	v_exp_f32_e32 v210, v129
	s_waitcnt lgkmcnt(5)
	v_mfma_f32_32x32x16_bf16 v[82:97], v[216:219], v[146:149], v[82:97]
	v_cvt_pk_bf16_f32 v114, v195, v197
	v_cvt_pk_bf16_f32 v115, v198, v201
	v_cvt_pk_bf16_f32 v116, v196, v199
	v_cvt_pk_bf16_f32 v117, v200, v202
	s_waitcnt lgkmcnt(4)
	v_mfma_f32_32x32x16_bf16 v[66:81], v[118:121], v[146:149], v[66:81]
	v_exp_f32_e32 v211, v98
	v_exp_f32_e32 v212, v99
	v_exp_f32_e32 v213, v100
	v_exp_f32_e32 v214, v101
	ds_read_b128 v[98:101], v184 offset:0x80
	ds_read_b128 v[118:121], v184 offset:0x1a80
	ds_read_b128 v[122:125], v184 offset:0xa0
	ds_read_b128 v[246:249], v184 offset:0x1aa0
	s_waitcnt lgkmcnt(4)
	v_mfma_f32_32x32x16_bf16 v[82:97], v[220:223], v[142:145], v[82:97]
	v_exp_f32_e32 v215, v102
	v_exp_f32_e32 v216, v103
	v_exp_f32_e32 v217, v104
	v_exp_f32_e32 v218, v105
	v_mfma_f32_32x32x16_bf16 v[66:81], v[228:231], v[142:145], v[66:81]
	v_cvt_pk_bf16_f32 v102, v203, v204
	v_cvt_pk_bf16_f32 v103, v205, v206
	v_cvt_pk_bf16_f32 v104, v207, v208
	v_cvt_pk_bf16_f32 v105, v209, v210
	v_mfma_f32_32x32x16_bf16 v[82:97], v[238:241], v[138:141], v[82:97]
	v_exp_f32_e32 v219, v106
	v_exp_f32_e32 v220, v107
	v_exp_f32_e32 v221, v108
	v_exp_f32_e32 v222, v109
	v_mfma_f32_32x32x16_bf16 v[66:81], v[242:245], v[138:141], v[66:81]
	v_exp_f32_e32 v223, v110
	v_exp_f32_e32 v234, v111
	v_exp_f32_e32 v235, v112
	v_exp_f32_e32 v236, v113
	s_waitcnt lgkmcnt(0)
	s_nop 0
	v_mfma_f32_32x32x16_bf16 v[82:97], v[98:101], v[134:137], v[82:97]
	v_cvt_pk_bf16_f32 v106, v211, v212
	v_cvt_pk_bf16_f32 v107, v213, v214
	v_cvt_pk_bf16_f32 v108, v215, v216
	v_cvt_pk_bf16_f32 v109, v217, v218
	v_mfma_f32_32x32x16_bf16 v[66:81], v[118:121], v[134:137], v[66:81]
	v_mfma_f32_32x32x16_bf16 v[82:97], v[122:125], v[130:133], v[82:97]
	v_cvt_pk_bf16_f32 v98, v219, v220
	v_cvt_pk_bf16_f32 v99, v221, v222
	v_cvt_pk_bf16_f32 v100, v223, v234
	v_cvt_pk_bf16_f32 v101, v235, v236
	ds_read_b64_tr_b16 v[126:127], v237 offset:0
	ds_read_b64_tr_b16 v[128:129], v237 offset:0x400
	ds_read_b64_tr_b16 v[122:123], v237 offset:0x200
	v_mfma_f32_32x32x16_bf16 v[66:81], v[246:249], v[130:133], v[66:81]
	ds_read_b64_tr_b16 v[124:125], v237 offset:0x600
	ds_read_b64_tr_b16 v[118:119], v237 offset:0x800
	ds_read_b64_tr_b16 v[120:121], v237 offset:0xc00
	ds_read_b64_tr_b16 v[110:111], v237 offset:0xa00
	ds_read_b64_tr_b16 v[112:113], v237 offset:0xe00
	s_cmp_ge_u32 s39, s38
	s_cselect_b64 s[18:19], -1, 0
	s_and_b64 vcc, exec, s[18:19]
	s_cbranch_vccnz .Lmy_y263
	buffer_load_dwordx4 v[162:165], v185, s[64:67], s52 offen
	buffer_load_dwordx4 v[166:169], v185, s[44:47], s52 offen
